# phase-4 weight conversion split between the halves (half 1, which had slack at the global barrier, converts 2048 of half 0's 6272 items)
# baseline (speedup 1.0000x reference)
.LBB0_986:
	s_and_b64 vcc, exec, s[2:3]
	s_cbranch_vccz .LBB0_1001
	s_cmp_lg_u64 s[76:77], 0
	s_cselect_b32 s98, 0x800, 0
	s_movk_i32 s99, 0x800
	s_cselect_b32 s99, 0x1880, s99
	v_mov_b32_e32 v0, v247
	s_nop 0
	v_readfirstlane_b32 s2, v0
	s_ashr_i32 s4, s2, 6
	v_readlane_b32 s2, v253, 6
	s_add_i32 s14, s4, s2
	s_add_i32 s14, s14, s98
	s_cmp_ge_i32 s14, s99
	s_cbranch_scc1 .LBB0_1002
	s_load_dwordx2 s[2:3], s[88:89], 0x8
	v_lshlrev_b32_e32 v1, 2, v0
	s_mulk_i32 s4, 0x4100
	v_bfe_u32 v65, v0, 4, 2
	v_and_b32_e32 v64, 60, v1
	v_bfe_u32 v73, v0, 3, 3
	v_lshlrev_b32_e32 v0, 3, v0
	s_add_i32 s4, s4, 0
	v_lshlrev_b32_e32 v1, 2, v64
	v_mul_u32_u24_e32 v2, 0x104, v65
	v_and_b32_e32 v0, 56, v0
	v_add3_u32 v72, s4, v1, v2
	v_mul_u32_u24_e32 v1, 0x104, v0
	v_lshlrev_b32_e32 v2, 2, v73
	v_add3_u32 v74, s4, v1, v2
	s_waitcnt lgkmcnt(0)
	s_add_u32 s4, s2, 0x4000
	v_lshlrev_b32_e32 v208, 1, v0
	s_addc_u32 s5, s3, 0
	v_lshl_add_u64 v[2:3], s[82:83], 0, v[208:209]
	s_mov_b64 s[6:7], 0x4000000
	v_lshl_add_u64 v[66:67], v[2:3], 0, s[6:7]
	s_add_u32 s6, s2, 0x2000
	s_addc_u32 s7, s3, 0
	s_mov_b64 s[8:9], 0x2000000
	s_cmp_lg_u64 s[2:3], 0
	v_or_b32_e32 v75, 8, v73
	v_or_b32_e32 v76, 16, v73
	v_or_b32_e32 v77, 24, v73
	v_or_b32_e32 v78, 32, v73
	v_or_b32_e32 v79, 40, v73
	v_or_b32_e32 v80, 48, v73
	v_or_b32_e32 v81, 56, v73
	v_lshl_add_u64 v[68:69], v[2:3], 0, s[8:9]
	s_cselect_b64 s[8:9], -1, 0
	v_lshlrev_b32_e32 v70, 1, v0
	s_branch .LBB0_992

.LBB0_991:
	s_add_i32 s10, s14, 0x400
	s_cmp_lt_i32 s10, s99
	s_mov_b32 s14, s10
	s_cbranch_scc0 .LBB0_1002
